# asm guide 7.11: GEMM1/GEMM2 first-half k-loops: next k-step's LDS stage/address math moved above the closing barrier (out of the post-barrier head); entry path computes it once
# baseline (speedup 1.0000x reference)
.LBB0_133:
	s_and_b64 vcc, exec, s[0:1]
	s_cbranch_vccz .LBB0_143
	s_nop 3
	v_lshlrev_b64 v[0:1], 11, v[192:193]
	v_lshl_add_u64 v[192:193], v[178:179], 0, v[0:1]
	v_lshlrev_b64 v[0:1], 11, v[190:191]
	v_lshl_add_u64 v[190:191], v[180:181], 0, v[0:1]
	v_lshlrev_b64 v[0:1], 11, v[188:189]
	v_lshl_add_u64 v[188:189], v[182:183], 0, v[0:1]
	v_lshlrev_b64 v[0:1], 11, v[186:187]
	v_lshl_add_u64 v[186:187], v[184:185], 0, v[0:1]
	v_mov_b32_e32 v0, 0
	s_mov_b32 s7, 0
	s_mov_b64 s[2:3], 0
	v_mov_b32_e32 v1, v0
	v_mov_b32_e32 v2, v0
	v_mov_b32_e32 v3, v0
	v_mov_b32_e32 v4, v0
	v_mov_b32_e32 v5, v0
	v_mov_b32_e32 v6, v0
	v_mov_b32_e32 v7, v0
	v_mov_b32_e32 v8, v0
	v_mov_b32_e32 v9, v0
	v_mov_b32_e32 v10, v0
	v_mov_b32_e32 v11, v0
	v_mov_b32_e32 v12, v0
	v_mov_b32_e32 v13, v0
	v_mov_b32_e32 v14, v0
	v_mov_b32_e32 v15, v0
	v_mov_b32_e32 v16, v0
	v_mov_b32_e32 v17, v0
	v_mov_b32_e32 v18, v0
	v_mov_b32_e32 v19, v0
	v_mov_b32_e32 v20, v0
	v_mov_b32_e32 v21, v0
	v_mov_b32_e32 v22, v0
	v_mov_b32_e32 v23, v0
	v_mov_b32_e32 v24, v0
	v_mov_b32_e32 v25, v0
	v_mov_b32_e32 v26, v0
	v_mov_b32_e32 v27, v0
	v_mov_b32_e32 v28, v0
	v_mov_b32_e32 v29, v0
	v_mov_b32_e32 v30, v0
	v_mov_b32_e32 v31, v0
	v_mov_b32_e32 v32, v0
	v_mov_b32_e32 v33, v0
	v_mov_b32_e32 v34, v0
	v_mov_b32_e32 v35, v0
	v_mov_b32_e32 v36, v0
	v_mov_b32_e32 v37, v0
	v_mov_b32_e32 v38, v0
	v_mov_b32_e32 v39, v0
	v_mov_b32_e32 v40, v0
	v_mov_b32_e32 v41, v0
	v_mov_b32_e32 v42, v0
	v_mov_b32_e32 v43, v0
	v_mov_b32_e32 v44, v0
	v_mov_b32_e32 v45, v0
	v_mov_b32_e32 v46, v0
	v_mov_b32_e32 v47, v0
	v_mov_b32_e32 v48, v0
	v_mov_b32_e32 v49, v0
	v_mov_b32_e32 v50, v0
	v_mov_b32_e32 v51, v0
	v_mov_b32_e32 v52, v0
	v_mov_b32_e32 v53, v0
	v_mov_b32_e32 v54, v0
	v_mov_b32_e32 v55, v0
	v_mov_b32_e32 v56, v0
	v_mov_b32_e32 v57, v0
	v_mov_b32_e32 v58, v0
	v_mov_b32_e32 v59, v0
	v_mov_b32_e32 v60, v0
	v_mov_b32_e32 v61, v0
	v_mov_b32_e32 v62, v0
	v_mov_b32_e32 v63, v0
	v_mov_b32_e32 v64, v0
	v_mov_b32_e32 v65, v0
	v_mov_b32_e32 v66, v0
	v_mov_b32_e32 v67, v0
	v_mov_b32_e32 v68, v0
	v_mov_b32_e32 v69, v0
	v_mov_b32_e32 v70, v0
	v_mov_b32_e32 v71, v0
	v_mov_b32_e32 v72, v0
	v_mov_b32_e32 v73, v0
	v_mov_b32_e32 v74, v0
	v_mov_b32_e32 v75, v0
	v_mov_b32_e32 v76, v0
	v_mov_b32_e32 v77, v0
	v_mov_b32_e32 v78, v0
	v_mov_b32_e32 v79, v0
	v_mov_b32_e32 v80, v0
	v_mov_b32_e32 v81, v0
	v_mov_b32_e32 v82, v0
	v_mov_b32_e32 v83, v0
	v_mov_b32_e32 v84, v0
	v_mov_b32_e32 v85, v0
	v_mov_b32_e32 v86, v0
	v_mov_b32_e32 v87, v0
	v_mov_b32_e32 v88, v0
	v_mov_b32_e32 v89, v0
	v_mov_b32_e32 v90, v0
	v_mov_b32_e32 v91, v0
	v_mov_b32_e32 v92, v0
	v_mov_b32_e32 v93, v0
	v_mov_b32_e32 v94, v0
	v_mov_b32_e32 v95, v0
	v_mov_b32_e32 v96, v0
	v_mov_b32_e32 v97, v0
	v_mov_b32_e32 v98, v0
	v_mov_b32_e32 v99, v0
	v_mov_b32_e32 v100, v0
	v_mov_b32_e32 v101, v0
	v_mov_b32_e32 v102, v0
	v_mov_b32_e32 v103, v0
	v_mov_b32_e32 v104, v0
	v_mov_b32_e32 v105, v0
	v_mov_b32_e32 v106, v0
	v_mov_b32_e32 v107, v0
	v_mov_b32_e32 v108, v0
	v_mov_b32_e32 v109, v0
	v_mov_b32_e32 v110, v0
	v_mov_b32_e32 v111, v0
	v_mov_b32_e32 v112, v0
	v_mov_b32_e32 v113, v0
	v_mov_b32_e32 v114, v0
	v_mov_b32_e32 v115, v0
	v_mov_b32_e32 v116, v0
	v_mov_b32_e32 v117, v0
	v_mov_b32_e32 v118, v0
	v_mov_b32_e32 v119, v0
	v_mov_b32_e32 v120, v0
	v_mov_b32_e32 v121, v0
	v_mov_b32_e32 v122, v0
	v_mov_b32_e32 v123, v0
	v_mov_b32_e32 v124, v0
	v_mov_b32_e32 v125, v0
	v_mov_b32_e32 v126, v0
	v_mov_b32_e32 v127, v0
	s_lshl_b32 s10, s52, 15
	v_or_b32_e32 v128, s10, v211
	v_add_u32_e32 v132, v128, v212
	s_branch .LBB0_136
.LBB0_135:
	s_add_i32 s0, s52, 1
	s_cmp_lg_u32 s52, 3
	s_cselect_b32 s52, s0, 0
	s_lshl_b32 s10, s52, 15
	v_or_b32_e32 v128, s10, v211
	v_add_u32_e32 v132, v128, v212
	s_add_i32 s7, s7, 1
	s_add_u32 s2, s2, 64
	s_addc_u32 s3, s3, 0
	s_cmpk_eq_i32 s2, 0x800
	s_barrier
	s_cbranch_scc1 .LBB0_142
.LBB0_136:
	ds_read_b128 v[172:175], v132
	ds_read_b128 v[168:171], v132 offset:1024
	ds_read_b128 v[164:167], v132 offset:2048
	ds_read_b128 v[160:163], v132 offset:3072
	ds_read_b128 v[156:159], v132 offset:4096
	ds_read_b128 v[152:155], v132 offset:5120
	ds_read_b128 v[136:139], v132 offset:6144
	ds_read_b128 v[128:131], v132 offset:7168
	v_add_u32_e32 v132, s41, v132
	ds_read_b128 v[144:147], v132 offset:16384
	ds_read_b128 v[148:151], v132 offset:17408
	ds_read_b128 v[140:143], v132 offset:18432
	ds_read_b128 v[132:135], v132 offset:19456
	s_cmp_lt_u32 s7, 29
	s_cselect_b64 s[0:1], -1, 0
	s_nor_b64 s[12:13], s[8:9], s[0:1]
	s_cbranch_scc1 .LBB0_138
	s_cmp_lg_u32 s7, 29
	s_cbranch_scc1 .Lgp_2
	v_lshl_add_u64 v[188:189], v[192:193], 0, s[2:3]
	v_lshl_add_u64 v[186:187], v[190:191], 0, s[2:3]

.LBB0_707:
	s_and_b64 vcc, exec, s[2:3]
	s_cbranch_vccz .LBB0_716
	s_nop 3
	v_add_u32_e32 v0, s52, v208
	v_ashrrev_i32_e32 v1, 31, v0
	v_lshlrev_b64 v[0:1], 11, v[0:1]
	v_lshl_add_u64 v[186:187], v[178:179], 0, v[0:1]
	v_add_u32_e32 v0, s82, v208
	v_ashrrev_i32_e32 v1, 31, v0
	v_lshlrev_b64 v[0:1], 11, v[0:1]
	v_lshl_add_u64 v[188:189], v[180:181], 0, v[0:1]
	v_add_u32_e32 v0, s14, v208
	v_ashrrev_i32_e32 v1, 31, v0
	v_lshlrev_b64 v[0:1], 11, v[0:1]
	v_lshl_add_u64 v[190:191], v[182:183], 0, v[0:1]
	v_add_u32_e32 v0, s15, v208
	v_ashrrev_i32_e32 v1, 31, v0
	v_lshlrev_b64 v[0:1], 11, v[0:1]
	v_lshl_add_u64 v[192:193], v[184:185], 0, v[0:1]
	v_mov_b32_e32 v0, 0
	s_mov_b32 s39, 0
	s_mov_b64 s[8:9], 0
	s_mov_b32 s64, s38
	v_mov_b32_e32 v1, v0
	v_mov_b32_e32 v2, v0
	v_mov_b32_e32 v3, v0
	v_mov_b32_e32 v4, v0
	v_mov_b32_e32 v5, v0
	v_mov_b32_e32 v6, v0
	v_mov_b32_e32 v7, v0
	v_mov_b32_e32 v8, v0
	v_mov_b32_e32 v9, v0
	v_mov_b32_e32 v10, v0
	v_mov_b32_e32 v11, v0
	v_mov_b32_e32 v12, v0
	v_mov_b32_e32 v13, v0
	v_mov_b32_e32 v14, v0
	v_mov_b32_e32 v15, v0
	v_mov_b32_e32 v16, v0
	v_mov_b32_e32 v17, v0
	v_mov_b32_e32 v18, v0
	v_mov_b32_e32 v19, v0
	v_mov_b32_e32 v20, v0
	v_mov_b32_e32 v21, v0
	v_mov_b32_e32 v22, v0
	v_mov_b32_e32 v23, v0
	v_mov_b32_e32 v24, v0
	v_mov_b32_e32 v25, v0
	v_mov_b32_e32 v26, v0
	v_mov_b32_e32 v27, v0
	v_mov_b32_e32 v28, v0
	v_mov_b32_e32 v29, v0
	v_mov_b32_e32 v30, v0
	v_mov_b32_e32 v31, v0
	v_mov_b32_e32 v32, v0
	v_mov_b32_e32 v33, v0
	v_mov_b32_e32 v34, v0
	v_mov_b32_e32 v35, v0
	v_mov_b32_e32 v36, v0
	v_mov_b32_e32 v37, v0
	v_mov_b32_e32 v38, v0
	v_mov_b32_e32 v39, v0
	v_mov_b32_e32 v40, v0
	v_mov_b32_e32 v41, v0
	v_mov_b32_e32 v42, v0
	v_mov_b32_e32 v43, v0
	v_mov_b32_e32 v44, v0
	v_mov_b32_e32 v45, v0
	v_mov_b32_e32 v46, v0
	v_mov_b32_e32 v47, v0
	v_mov_b32_e32 v48, v0
	v_mov_b32_e32 v49, v0
	v_mov_b32_e32 v50, v0
	v_mov_b32_e32 v51, v0
	v_mov_b32_e32 v52, v0
	v_mov_b32_e32 v53, v0
	v_mov_b32_e32 v54, v0
	v_mov_b32_e32 v55, v0
	v_mov_b32_e32 v56, v0
	v_mov_b32_e32 v57, v0
	v_mov_b32_e32 v58, v0
	v_mov_b32_e32 v59, v0
	v_mov_b32_e32 v60, v0
	v_mov_b32_e32 v61, v0
	v_mov_b32_e32 v62, v0
	v_mov_b32_e32 v63, v0
	v_mov_b32_e32 v64, v0
	v_mov_b32_e32 v65, v0
	v_mov_b32_e32 v66, v0
	v_mov_b32_e32 v67, v0
	v_mov_b32_e32 v68, v0
	v_mov_b32_e32 v69, v0
	v_mov_b32_e32 v70, v0
	v_mov_b32_e32 v71, v0
	v_mov_b32_e32 v72, v0
	v_mov_b32_e32 v73, v0
	v_mov_b32_e32 v74, v0
	v_mov_b32_e32 v75, v0
	v_mov_b32_e32 v76, v0
	v_mov_b32_e32 v77, v0
	v_mov_b32_e32 v78, v0
	v_mov_b32_e32 v79, v0
	v_mov_b32_e32 v80, v0
	v_mov_b32_e32 v81, v0
	v_mov_b32_e32 v82, v0
	v_mov_b32_e32 v83, v0
	v_mov_b32_e32 v84, v0
	v_mov_b32_e32 v85, v0
	v_mov_b32_e32 v86, v0
	v_mov_b32_e32 v87, v0
	v_mov_b32_e32 v88, v0
	v_mov_b32_e32 v89, v0
	v_mov_b32_e32 v90, v0
	v_mov_b32_e32 v91, v0
	v_mov_b32_e32 v92, v0
	v_mov_b32_e32 v93, v0
	v_mov_b32_e32 v94, v0
	v_mov_b32_e32 v95, v0
	v_mov_b32_e32 v96, v0
	v_mov_b32_e32 v97, v0
	v_mov_b32_e32 v98, v0
	v_mov_b32_e32 v99, v0
	v_mov_b32_e32 v100, v0
	v_mov_b32_e32 v101, v0
	v_mov_b32_e32 v102, v0
	v_mov_b32_e32 v103, v0
	v_mov_b32_e32 v104, v0
	v_mov_b32_e32 v105, v0
	v_mov_b32_e32 v106, v0
	v_mov_b32_e32 v107, v0
	v_mov_b32_e32 v108, v0
	v_mov_b32_e32 v109, v0
	v_mov_b32_e32 v110, v0
	v_mov_b32_e32 v111, v0
	v_mov_b32_e32 v112, v0
	v_mov_b32_e32 v113, v0
	v_mov_b32_e32 v114, v0
	v_mov_b32_e32 v115, v0
	v_mov_b32_e32 v116, v0
	v_mov_b32_e32 v117, v0
	v_mov_b32_e32 v118, v0
	v_mov_b32_e32 v119, v0
	v_mov_b32_e32 v120, v0
	v_mov_b32_e32 v121, v0
	v_mov_b32_e32 v122, v0
	v_mov_b32_e32 v123, v0
	v_mov_b32_e32 v124, v0
	v_mov_b32_e32 v125, v0
	v_mov_b32_e32 v126, v0
	v_mov_b32_e32 v127, v0
	s_lshl_b32 s54, s64, 15
	v_or_b32_e32 v128, s54, v202
	v_add_u32_e32 v132, v128, v203
	s_branch .LBB0_710
.LBB0_709:
	s_add_i32 s2, s64, 1
	s_cmp_lg_u32 s64, 3
	s_cselect_b32 s64, s2, 0
	s_lshl_b32 s54, s64, 15
	v_or_b32_e32 v128, s54, v202
	v_add_u32_e32 v132, v128, v203
	s_add_i32 s39, s39, 1
	s_add_u32 s8, s8, 64
	s_addc_u32 s9, s9, 0
	s_cmpk_eq_i32 s8, 0x800
	s_barrier
	s_cbranch_scc1 .LBB0_716
.LBB0_710:
	ds_read_b128 v[172:175], v132
	ds_read_b128 v[168:171], v132 offset:1024
	ds_read_b128 v[164:167], v132 offset:2048
	ds_read_b128 v[160:163], v132 offset:3072
	ds_read_b128 v[156:159], v132 offset:4096
	ds_read_b128 v[152:155], v132 offset:5120
	ds_read_b128 v[136:139], v132 offset:6144
	ds_read_b128 v[128:131], v132 offset:7168
	v_add_u32_e32 v132, s36, v132
	ds_read_b128 v[144:147], v132 offset:16384
	ds_read_b128 v[148:151], v132 offset:17408
	ds_read_b128 v[140:143], v132 offset:18432
	ds_read_b128 v[132:135], v132 offset:19456
	s_cmp_lt_u32 s39, 29
	s_cselect_b64 s[2:3], -1, 0
	s_nor_b64 s[12:13], s[16:17], s[2:3]
	s_cbranch_scc1 .LBB0_712
	s_cmp_lg_u32 s39, 29
	s_cbranch_scc1 .Lgp_4
	v_lshl_add_u64 v[190:191], v[186:187], 0, s[8:9]
	v_lshl_add_u64 v[192:193], v[188:189], 0, s[8:9]

.LBB0_726:
	s_and_b64 vcc, exec, s[2:3]
	s_cbranch_vccz .LBB0_736
	s_nop 3
	v_lshlrev_b64 v[0:1], 11, v[192:193]
	v_lshl_add_u64 v[192:193], v[178:179], 0, v[0:1]
	v_lshlrev_b64 v[0:1], 11, v[190:191]
	v_lshl_add_u64 v[190:191], v[180:181], 0, v[0:1]
	v_lshlrev_b64 v[0:1], 11, v[188:189]
	v_lshl_add_u64 v[188:189], v[182:183], 0, v[0:1]
	v_lshlrev_b64 v[0:1], 11, v[186:187]
	v_lshl_add_u64 v[186:187], v[184:185], 0, v[0:1]
	v_mov_b32_e32 v0, 0
	s_mov_b32 s12, 0
	s_mov_b64 s[2:3], 0
	v_mov_b32_e32 v1, v0
	v_mov_b32_e32 v2, v0
	v_mov_b32_e32 v3, v0
	v_mov_b32_e32 v4, v0
	v_mov_b32_e32 v5, v0
	v_mov_b32_e32 v6, v0
	v_mov_b32_e32 v7, v0
	v_mov_b32_e32 v8, v0
	v_mov_b32_e32 v9, v0
	v_mov_b32_e32 v10, v0
	v_mov_b32_e32 v11, v0
	v_mov_b32_e32 v12, v0
	v_mov_b32_e32 v13, v0
	v_mov_b32_e32 v14, v0
	v_mov_b32_e32 v15, v0
	v_mov_b32_e32 v16, v0
	v_mov_b32_e32 v17, v0
	v_mov_b32_e32 v18, v0
	v_mov_b32_e32 v19, v0
	v_mov_b32_e32 v20, v0
	v_mov_b32_e32 v21, v0
	v_mov_b32_e32 v22, v0
	v_mov_b32_e32 v23, v0
	v_mov_b32_e32 v24, v0
	v_mov_b32_e32 v25, v0
	v_mov_b32_e32 v26, v0
	v_mov_b32_e32 v27, v0
	v_mov_b32_e32 v28, v0
	v_mov_b32_e32 v29, v0
	v_mov_b32_e32 v30, v0
	v_mov_b32_e32 v31, v0
	v_mov_b32_e32 v32, v0
	v_mov_b32_e32 v33, v0
	v_mov_b32_e32 v34, v0
	v_mov_b32_e32 v35, v0
	v_mov_b32_e32 v36, v0
	v_mov_b32_e32 v37, v0
	v_mov_b32_e32 v38, v0
	v_mov_b32_e32 v39, v0
	v_mov_b32_e32 v40, v0
	v_mov_b32_e32 v41, v0
	v_mov_b32_e32 v42, v0
	v_mov_b32_e32 v43, v0
	v_mov_b32_e32 v44, v0
	v_mov_b32_e32 v45, v0
	v_mov_b32_e32 v46, v0
	v_mov_b32_e32 v47, v0
	v_mov_b32_e32 v48, v0
	v_mov_b32_e32 v49, v0
	v_mov_b32_e32 v50, v0
	v_mov_b32_e32 v51, v0
	v_mov_b32_e32 v52, v0
	v_mov_b32_e32 v53, v0
	v_mov_b32_e32 v54, v0
	v_mov_b32_e32 v55, v0
	v_mov_b32_e32 v56, v0
	v_mov_b32_e32 v57, v0
	v_mov_b32_e32 v58, v0
	v_mov_b32_e32 v59, v0
	v_mov_b32_e32 v60, v0
	v_mov_b32_e32 v61, v0
	v_mov_b32_e32 v62, v0
	v_mov_b32_e32 v63, v0
	v_mov_b32_e32 v64, v0
	v_mov_b32_e32 v65, v0
	v_mov_b32_e32 v66, v0
	v_mov_b32_e32 v67, v0
	v_mov_b32_e32 v68, v0
	v_mov_b32_e32 v69, v0
	v_mov_b32_e32 v70, v0
	v_mov_b32_e32 v71, v0
	v_mov_b32_e32 v72, v0
	v_mov_b32_e32 v73, v0
	v_mov_b32_e32 v74, v0
	v_mov_b32_e32 v75, v0
	v_mov_b32_e32 v76, v0
	v_mov_b32_e32 v77, v0
	v_mov_b32_e32 v78, v0
	v_mov_b32_e32 v79, v0
	v_mov_b32_e32 v80, v0
	v_mov_b32_e32 v81, v0
	v_mov_b32_e32 v82, v0
	v_mov_b32_e32 v83, v0
	v_mov_b32_e32 v84, v0
	v_mov_b32_e32 v85, v0
	v_mov_b32_e32 v86, v0
	v_mov_b32_e32 v87, v0
	v_mov_b32_e32 v88, v0
	v_mov_b32_e32 v89, v0
	v_mov_b32_e32 v90, v0
	v_mov_b32_e32 v91, v0
	v_mov_b32_e32 v92, v0
	v_mov_b32_e32 v93, v0
	v_mov_b32_e32 v94, v0
	v_mov_b32_e32 v95, v0
	v_mov_b32_e32 v96, v0
	v_mov_b32_e32 v97, v0
	v_mov_b32_e32 v98, v0
	v_mov_b32_e32 v99, v0
	v_mov_b32_e32 v100, v0
	v_mov_b32_e32 v101, v0
	v_mov_b32_e32 v102, v0
	v_mov_b32_e32 v103, v0
	v_mov_b32_e32 v104, v0
	v_mov_b32_e32 v105, v0
	v_mov_b32_e32 v106, v0
	v_mov_b32_e32 v107, v0
	v_mov_b32_e32 v108, v0
	v_mov_b32_e32 v109, v0
	v_mov_b32_e32 v110, v0
	v_mov_b32_e32 v111, v0
	v_mov_b32_e32 v112, v0
	v_mov_b32_e32 v113, v0
	v_mov_b32_e32 v114, v0
	v_mov_b32_e32 v115, v0
	v_mov_b32_e32 v116, v0
	v_mov_b32_e32 v117, v0
	v_mov_b32_e32 v118, v0
	v_mov_b32_e32 v119, v0
	v_mov_b32_e32 v120, v0
	v_mov_b32_e32 v121, v0
	v_mov_b32_e32 v122, v0
	v_mov_b32_e32 v123, v0
	v_mov_b32_e32 v124, v0
	v_mov_b32_e32 v125, v0
	v_mov_b32_e32 v126, v0
	v_mov_b32_e32 v127, v0
	s_lshl_b32 s13, s38, 15
	v_or_b32_e32 v128, s13, v202
	v_add_u32_e32 v132, v128, v203
	s_branch .LBB0_729
.LBB0_728:
	s_add_i32 s0, s38, 1
	s_cmp_lg_u32 s38, 3
	s_cselect_b32 s38, s0, 0
	s_lshl_b32 s13, s38, 15
	v_or_b32_e32 v128, s13, v202
	v_add_u32_e32 v132, v128, v203
	s_add_i32 s12, s12, 1
	s_add_u32 s2, s2, 64
	s_addc_u32 s3, s3, 0
	s_cmpk_eq_i32 s2, 0x800
	s_barrier
	s_cbranch_scc1 .LBB0_735
.LBB0_729:
	ds_read_b128 v[172:175], v132
	ds_read_b128 v[168:171], v132 offset:1024
	ds_read_b128 v[164:167], v132 offset:2048
	ds_read_b128 v[160:163], v132 offset:3072
	ds_read_b128 v[156:159], v132 offset:4096
	ds_read_b128 v[152:155], v132 offset:5120
	ds_read_b128 v[136:139], v132 offset:6144
	ds_read_b128 v[128:131], v132 offset:7168
	v_add_u32_e32 v132, s36, v132
	ds_read_b128 v[144:147], v132 offset:16384
	ds_read_b128 v[148:151], v132 offset:17408
	ds_read_b128 v[140:143], v132 offset:18432
	ds_read_b128 v[132:135], v132 offset:19456
	s_cmp_lt_u32 s12, 29
	s_cselect_b64 s[0:1], -1, 0
	s_nor_b64 s[8:9], s[16:17], s[0:1]
	s_cbranch_scc1 .LBB0_731
	s_cmp_lg_u32 s12, 29
	s_cbranch_scc1 .Lgp_6
	v_lshl_add_u64 v[188:189], v[192:193], 0, s[2:3]
	v_lshl_add_u64 v[186:187], v[190:191], 0, s[2:3]
